# grid barrier acquire from an idle wave: in seams L0-L8 the L1 invalidate is issued and waited for by wave 1 (parked anyway), the barrier thread never waits for it (on combined+final version)
# speedup vs baseline: 1.0081x; 1.0053x over previous
; __device__ __forceinline__ unsigned xb_ld(unsigned* p)              { return __hip_atomic_load(p, __ATOMIC_RELAXED, __HIP_MEMORY_SCOPE_AGENT); }
; __device__ __forceinline__ unsigned xb_add(unsigned* p, unsigned v) { return __hip_atomic_fetch_add(p, v, __ATOMIC_RELAXED, __HIP_MEMORY_SCOPE_AGENT); }
; #define XB_SPIN(cond, bar) do { unsigned _sp = 0; while (cond) { __builtin_amdgcn_s_sleep(1); \
;     if ((++_sp & 255u) == 0u) { if (xb_ld(&(bar)[XB_TMO])) break; if (_sp > XB_SPIN_CAP) { atomicAdd(&(bar)[XB_TMO], 1u); break; } } } } while (0)
; __device__ __forceinline__ void xcd_barrier(const XcdBarrier& b) {
;     ...
;             __builtin_amdgcn_fence(__ATOMIC_ACQUIRE, "agent");
;             xb_add(&bar[XB_XGEN(b.x)], 1u);
;             asm volatile("s_waitcnt vmcnt(0)" ::: "memory");
;         } else {
;             XB_SPIN(xb_ld(&bar[XB_XGEN(b.x)]) == gen, bar);
;             __builtin_amdgcn_fence(__ATOMIC_ACQUIRE, "agent");
;             asm volatile("s_waitcnt vmcnt(0)" ::: "memory");
;         }
;     }
;     __syncthreads();
.LBB0_584:
	s_or_b64 exec, exec, s[4:5]
	v_readlane_b32 s4, v245, 50
	v_readlane_b32 s5, v245, 51
	s_waitcnt vmcnt(0)
	s_nop 2
	s_waitcnt vmcnt(0)
	s_branch .LBB0_585
.Leinv3_L0:
	s_or_b64 exec, exec, s[0:1]
	v_readfirstlane_b32 s4, v0
	s_lshr_b32 s4, s4, 6
	s_cmp_lg_u32 s4, 1
	s_cbranch_scc1 .LBB0_585
	buffer_inv sc1
	s_waitcnt vmcnt(0)
